# skip term split between the two directions by chunk parity (each workgroup adds it on every other chunk)
# speedup vs baseline: 1.0004x; 1.0004x over previous
.Lm_fwd_1:
	s_lshl_b32 s15, s7, 23
	s_lshl_b32 s96, s6, 22
	s_add_u32 s15, s15, s96
	s_lshl_b32 s96, s11, 16
	s_add_u32 s15, s15, s96
	s_add_u32 s15, s15, 0x1b000000
	s_add_u32 s38, s36, s15
	s_addc_u32 s39, s37, 0
	s_lshl_b32 s15, s8, 1
	s_add_u32 s15, s15, s5
	s_lshl_b32 s15, s15, 20
	s_lshl_b32 s96, s6, 19
	s_add_u32 s15, s15, s96
	s_lshl_b32 s96, s11, 13
	s_add_u32 s15, s15, s96
	s_add_u32 s15, s15, 0x17000000
	s_add_u32 s40, s36, s15
	s_addc_u32 s41, s37, 0
	s_lshl_b32 s15, s6, 21
	s_add_u32 s15, s15, s9
	s_lshl_b32 s96, s11, 15
	s_add_u32 s15, s15, s96
	s_add_u32 s15, s15, 0x1f000000
	s_add_u32 s42, s36, s15
	s_addc_u32 s43, s37, 0
	s_lshl_b32 s15, s6, 25
	s_lshl_b32 s96, s8, 7
	s_add_u32 s15, s15, s96
	s_lshl_b32 s96, s5, 6
	s_add_u32 s15, s15, s96
	s_lshl_b32 s96, s11, 19
	s_add_u32 s15, s15, s96
	s_lshl_b32 s96, s51, 26
	s_add_u32 s15, s15, s96
	s_add_u32 s15, s15, 0xf000000
	s_add_u32 s44, s36, s15
	s_addc_u32 s45, s37, 0
	s_add_u32 s4, s3, 1
	s_sub_i32 s5, 4, s3
	s_movk_i32 s6, 0x2200
	s_mov_b32 s7, 0xffffde00
	s_movk_i32 s8, 0x80
	s_mov_b32 s9, 0xffffff80
	s_movk_i32 s15, 0x800
	s_mov_b32 s96, 0xfffff800
	s_cmp_eq_u32 s51, 0
	s_cselect_b32 s52, s4, s5
	s_cselect_b32 s53, s7, s6
	s_cselect_b32 s54, s9, s8
	s_cselect_b32 s13, s96, s15
	s_cselect_b32 s21, 124, 0
	s_waitcnt lgkmcnt(0)
	v_mov_b32_e32 v1, s10
	v_mul_f32_e32 v1, 0x3fb8aa3b, v1
	v_exp_f32_e32 v1, v1
	s_nop 0
	v_xor_b32_e32 v1, 0x80000000, v1
	s_nop 0
	v_readfirstlane_b32 s62, v1
	v_and_b32_e32 v116, 31, v175
	v_bfe_u32 v117, v175, 5, 1
	v_bfe_u32 v118, v175, 2, 2
	v_and_b32_e32 v119, 3, v175
	v_bfe_u32 v120, v175, 4, 1
	v_and_b32_e32 v121, 63, v175
	v_lshlrev_b32_e32 v122, 5, v120
	v_lshl_add_u32 v122, v119, 3, v122
	v_lshl_add_u32 v123, v117, 3, v118
	s_cmp_lt_u32 s3, 4
	s_cbranch_scc0 .Lm_setup_hi_2
	s_lshl_b32 s4, s3, 5
	v_add_u32_e32 v128, s4, v116
	v_lshlrev_b32_e32 v129, 4, v117
	v_lshrrev_b32_e32 v124, 4, v121
	v_and_b32_e32 v125, 15, v121
	v_lshlrev_b32_e32 v125, 4, v125
	v_lshlrev_b32_e32 v126, 3, v124
	s_lshl_b32 s4, s3, 5
	v_add_u32_e32 v127, s4, v126
	v_lshl_add_u32 v164, v127, 9, v125
	v_add_u32_e32 v164, 0x100, v164
	s_mul_i32 s4, s3, 0x2200
	s_add_u32 s4, s4, 0x11000
	v_mad_u32_u24 v166, v126, s59, v125
	v_add_u32_e32 v166, s4, v166
	v_mad_u32_u24 v167, v116, s59, v129
	v_add_u32_e32 v167, s4, v167
	v_lshlrev_b32_e32 v130, 3, v117
	v_mov_b32_e32 v131, 80
	v_mov_b32_e32 v131, 0x90
	v_lshlrev_b32_e32 v130, 4, v117
	v_mad_u32_u24 v168, v116, v131, v130
	v_add_u32_e32 v168, s4, v168
	v_lshrrev_b32_e32 v124, 2, v121
	v_and_b32_e32 v125, 3, v121
	v_lshlrev_b32_e32 v126, 5, v125
	v_lshlrev_b32_e32 v125, 4, v125
	v_mad_u32_u24 v169, v124, v131, v126
	v_add_u32_e32 v169, s4, v169
	s_lshl_b32 s4, s3, 5
	v_add_u32_e32 v124, s4, v124
	v_lshl_add_u32 v170, v124, 12, v125
	v_lshl_add_u32 v173, v124, 6, v125
	v_add_u32_e32 v171, 0x10000, v170
	v_mad_u32_u24 v165, v128, s59, v129
	v_mad_u32_u24 v130, v116, s59, v129
	v_add_u32_e32 v210, 0x1e800, v130
	v_lshlrev_b32_e32 v130, 2, v128
	v_add_u32_e32 v211, 0x22c00, v130
	v_lshlrev_b32_e32 v130, 3, v117
	v_lshl_add_u32 v212, v128, 12, v130
	s_lshl_b32 s4, s3, 7
	s_add_u32 s4, s4, 0x22c00
	v_add_u32_e32 v217, s4, v129
	s_lshl_b32 s4, s3, 7
	s_add_u32 s4, s4, 0x1d800
	v_add_u32_e32 v172, s4, v129
	s_cmp_eq_u32 s51, 0
	s_cselect_b32 s5, 124, 0
	s_lshl_b32 s4, s3, 7
	s_add_u32 s4, s4, s5
	s_add_u32 s4, s4, 0x22c00
	v_mov_b32_e32 v209, s4
	v_lshl_add_u32 v130, v117, 2, v118
	s_lshl_b32 s4, s3, 5
	v_add_u32_e32 v130, s4, v130
	v_mad_u32_u24 v130, v130, s60, v122
	v_add_u32_e32 v222, 0x19800, v130
	v_lshlrev_b32_e32 v129, 2, v117
	s_cmp_eq_u32 s51, 0
	s_cbranch_scc0 .Lm_mbwd_4
	v_add_u32_e32 v130, 0, v129
	v_cmp_le_u32_e64 s[64:65], v130, v116
	v_add_u32_e32 v130, 1, v129
	v_cmp_le_u32_e64 s[66:67], v130, v116
	v_add_u32_e32 v130, 2, v129
	v_cmp_le_u32_e64 s[68:69], v130, v116
	v_add_u32_e32 v130, 3, v129
	v_cmp_le_u32_e64 s[70:71], v130, v116
	v_add_u32_e32 v130, 8, v129
	v_cmp_le_u32_e64 s[72:73], v130, v116
	v_add_u32_e32 v130, 9, v129
	v_cmp_le_u32_e64 s[74:75], v130, v116
	v_add_u32_e32 v130, 10, v129
	v_cmp_le_u32_e64 s[76:77], v130, v116
	v_add_u32_e32 v130, 11, v129
	v_cmp_le_u32_e64 s[78:79], v130, v116
	v_add_u32_e32 v130, 16, v129
	v_cmp_le_u32_e64 s[80:81], v130, v116
	v_add_u32_e32 v130, 17, v129
	v_cmp_le_u32_e64 s[82:83], v130, v116
	v_add_u32_e32 v130, 18, v129
	v_cmp_le_u32_e64 s[84:85], v130, v116
	v_add_u32_e32 v130, 19, v129
	v_cmp_le_u32_e64 s[86:87], v130, v116
	v_add_u32_e32 v130, 24, v129
	v_cmp_le_u32_e64 s[88:89], v130, v116
	v_add_u32_e32 v130, 25, v129
	v_cmp_le_u32_e64 s[90:91], v130, v116
	v_add_u32_e32 v130, 26, v129
	v_cmp_le_u32_e64 s[92:93], v130, v116
	v_add_u32_e32 v130, 27, v129
	v_cmp_le_u32_e64 s[94:95], v130, v116
	s_branch .Lm_mdone_5

.Lm_loop:
	s_and_b32 s19, s50, 3
	s_lshl_b32 s19, s19, 9
	s_add_u32 s20, s50, 2
	s_and_b32 s20, s20, 3
	s_lshl_b32 s20, s20, 9
	s_cmp_lt_u32 s3, 4
	s_cbranch_scc0 .Lm_hi_14
	v_mov_b32_e32 v223, v165
	v_add_u32_e32 v224, s14, v217
	v_add_u32_e32 v208, s19, v172
	v_add_u32_e32 v216, s14, v209
	v_mov_b32_e32 v225, v222
	v_add_u32_e32 v1, s14, v211
	ds_read_b128 v[176:179], v167 offset:0
	ds_read_b128 v[180:183], v167 offset:32
	ds_read_b128 v[184:187], v167 offset:64
	ds_read_b128 v[188:191], v167 offset:96
	ds_read_b128 v[192:195], v167 offset:128
	ds_read_b128 v[196:199], v167 offset:160
	ds_read_b128 v[200:203], v167 offset:192
	ds_read_b128 v[204:207], v167 offset:224
	ds_read_b128 v[148:151], v223 offset:0
	ds_read_b128 v[152:155], v223 offset:32
	ds_read_b128 v[156:159], v223 offset:64
	ds_read_b128 v[160:163], v223 offset:96
	s_waitcnt lgkmcnt(11)
	s_waitcnt lgkmcnt(3)
	v_mfma_f32_32x32x16_bf16 v[116:131], v[148:151], v[176:179], 0
	ds_read_b128 v[148:151], v223 offset:128
	v_fma_f32 v76, v92, v3, v76
	v_fma_f32 v77, v93, v3, v77
	v_fma_f32 v78, v94, v3, v78
	s_waitcnt lgkmcnt(3)
	v_mfma_f32_32x32x16_bf16 v[116:131], v[152:155], v[180:183], v[116:131]
	ds_read_b128 v[152:155], v223 offset:160
	v_fma_f32 v79, v95, v3, v79
	v_fma_f32 v80, v96, v3, v80
	v_fma_f32 v81, v97, v3, v81
	s_waitcnt lgkmcnt(3)
	v_mfma_f32_32x32x16_bf16 v[116:131], v[156:159], v[184:187], v[116:131]
	ds_read_b128 v[156:159], v223 offset:192
	v_fma_f32 v82, v98, v3, v82
	v_fma_f32 v83, v99, v3, v83
	v_fma_f32 v84, v100, v3, v84
	s_waitcnt lgkmcnt(3)
	v_mfma_f32_32x32x16_bf16 v[116:131], v[160:163], v[188:191], v[116:131]
	ds_read_b128 v[160:163], v223 offset:224
	v_fma_f32 v85, v101, v3, v85
	v_fma_f32 v86, v102, v3, v86
	v_fma_f32 v87, v103, v3, v87
	ds_read_b128 v[234:237], v224 offset:0
	ds_read_b128 v[238:241], v224 offset:32
	ds_read_b128 v[242:245], v224 offset:64
	ds_read_b128 v[246:249], v224 offset:96
	ds_read_b32 v250, v1
	s_waitcnt lgkmcnt(8)
	v_mfma_f32_32x32x16_bf16 v[116:131], v[148:151], v[192:195], v[116:131]
	v_fma_f32 v88, v104, v3, v88
	v_fma_f32 v89, v105, v3, v89
	v_fma_f32 v90, v106, v3, v90
	s_waitcnt lgkmcnt(7)
	v_mfma_f32_32x32x16_bf16 v[116:131], v[152:155], v[196:199], v[116:131]
	v_fma_f32 v91, v107, v3, v91
	s_waitcnt lgkmcnt(6)
	v_mfma_f32_32x32x16_bf16 v[116:131], v[156:159], v[200:203], v[116:131]
	s_waitcnt lgkmcnt(5)
	v_mfma_f32_32x32x16_bf16 v[116:131], v[160:163], v[204:207], v[116:131]
	s_cmp_eq_u32 s52, 1
	s_cbranch_scc1 .Lm_yfin1_19
	ds_write_b128 v168, v[76:79] offset:0
	ds_write_b128 v168, v[80:83] offset:32
	ds_write_b128 v168, v[84:87] offset:64
	ds_write_b128 v168, v[88:91] offset:96
	ds_read_b64_tr_b16 v[36:37], v225 offset:0
	ds_read_b64_tr_b16 v[38:39], v225 offset:512
	ds_read_b64_tr_b16 v[72:73], v225 offset:1024
	ds_read_b64_tr_b16 v[74:75], v225 offset:1536
	v_add_u32_e32 v223, s53, v223
	v_add_u32_e32 v208, s54, v208
	v_add_u32_e32 v216, s54, v216
	v_add_u32_e32 v225, s13, v225
	s_waitcnt lgkmcnt(9)
	s_waitcnt lgkmcnt(8)
	ds_read_b128 v[148:151], v223 offset:0
	ds_read_b128 v[152:155], v223 offset:32
	ds_read_b128 v[156:159], v223 offset:64
	ds_read_b128 v[160:163], v223 offset:96
	s_waitcnt lgkmcnt(3)
	v_mfma_f32_32x32x16_bf16 v[132:147], v[148:151], v[176:179], 0
	ds_read_b128 v[148:151], v223 offset:128
	ds_read_b128 v[92:95], v169 offset:0
	ds_read_b128 v[96:99], v169 offset:16
	ds_read_b128 v[100:103], v169 offset:2304
	ds_read_b128 v[104:107], v169 offset:2320
	v_sub_f32_e32 v234, v250, v234
	v_sub_f32_e32 v235, v250, v235
	v_sub_f32_e32 v236, v250, v236
	v_sub_f32_e32 v237, v250, v237
	v_sub_f32_e32 v238, v250, v238
	v_sub_f32_e32 v239, v250, v239
	v_sub_f32_e32 v240, v250, v240
	v_sub_f32_e32 v241, v250, v241
	v_sub_f32_e32 v242, v250, v242
	s_waitcnt lgkmcnt(7)
	v_mfma_f32_32x32x16_bf16 v[132:147], v[152:155], v[180:183], v[132:147]
	ds_read_b128 v[152:155], v223 offset:160
	v_sub_f32_e32 v243, v250, v243
	v_sub_f32_e32 v244, v250, v244
	v_sub_f32_e32 v245, v250, v245
	v_sub_f32_e32 v246, v250, v246
	v_sub_f32_e32 v247, v250, v247
	v_sub_f32_e32 v248, v250, v248
	v_sub_f32_e32 v249, v250, v249
	v_exp_f32_e32 v234, v234
	v_exp_f32_e32 v235, v235
	s_waitcnt lgkmcnt(7)
	v_mfma_f32_32x32x16_bf16 v[132:147], v[156:159], v[184:187], v[132:147]
	ds_read_b128 v[156:159], v223 offset:192
	v_exp_f32_e32 v236, v236
	v_exp_f32_e32 v237, v237
	v_exp_f32_e32 v238, v238
	v_exp_f32_e32 v239, v239
	v_exp_f32_e32 v240, v240
	v_exp_f32_e32 v241, v241
	v_exp_f32_e32 v242, v242
	v_exp_f32_e32 v243, v243
	v_exp_f32_e32 v244, v244
	s_waitcnt lgkmcnt(7)
	v_mfma_f32_32x32x16_bf16 v[132:147], v[160:163], v[188:191], v[132:147]
	ds_read_b128 v[160:163], v223 offset:224
	s_waitcnt lgkmcnt(3)
	v_cvt_pk_bf16_f32 v92, v92, v93
	v_cvt_pk_bf16_f32 v93, v94, v95
	v_cvt_pk_bf16_f32 v94, v96, v97
	v_cvt_pk_bf16_f32 v95, v98, v99
	v_cvt_pk_bf16_f32 v100, v100, v101
	v_cvt_pk_bf16_f32 v101, v102, v103
	v_cvt_pk_bf16_f32 v102, v104, v105
	v_cvt_pk_bf16_f32 v103, v106, v107
	global_store_dwordx4 v170, v[92:95], s[44:45]
	global_store_dwordx4 v171, v[100:103], s[44:45]
	s_cmp_lg_u32 s50, 0
	s_cselect_b32 s4, s49, 0
	s_cselect_b32 s5, s55, 0
	s_cselect_b32 s6, s47, 0
	s_add_u32 s44, s44, s4
	s_addc_u32 s45, s45, s5
	s_add_u32 s40, s40, s6
	s_addc_u32 s41, s41, s5
	s_waitcnt vmcnt(12)
	v_exp_f32_e32 v245, v245
	v_exp_f32_e32 v246, v246
	v_exp_f32_e32 v247, v247
	v_exp_f32_e32 v248, v248
	v_exp_f32_e32 v249, v249
	v_mul_f32_e32 v116, v116, v234
	v_mul_f32_e32 v117, v117, v235
	v_mul_f32_e32 v118, v118, v236
	v_mul_f32_e32 v119, v119, v237
	v_mfma_f32_32x32x16_bf16 v[132:147], v[148:151], v[192:195], v[132:147]
	ds_write_b128 v166, v[40:43] offset:0
	ds_write_b128 v166, v[44:47] offset:272
	v_mul_f32_e32 v120, v120, v238
	v_mul_f32_e32 v121, v121, v239
	v_mul_f32_e32 v122, v122, v240
	v_mul_f32_e32 v123, v123, v241
	v_mul_f32_e32 v124, v124, v242
	v_mul_f32_e32 v125, v125, v243
	v_mul_f32_e32 v126, v126, v244
	v_mul_f32_e32 v127, v127, v245
	v_mul_f32_e32 v128, v128, v246
	s_waitcnt lgkmcnt(4)
	v_mfma_f32_32x32x16_bf16 v[132:147], v[152:155], v[196:199], v[132:147]
	ds_write_b128 v166, v[48:51] offset:544
	ds_write_b128 v166, v[52:55] offset:816
	v_mul_f32_e32 v129, v129, v247
	v_mul_f32_e32 v130, v130, v248
	v_mul_f32_e32 v131, v131, v249
	v_cndmask_b32_e64 v116, 0, v116, s[64:65]
	v_cndmask_b32_e64 v117, 0, v117, s[66:67]
	v_cndmask_b32_e64 v118, 0, v118, s[68:69]
	v_cndmask_b32_e64 v119, 0, v119, s[70:71]
	v_cndmask_b32_e64 v120, 0, v120, s[72:73]
	v_cndmask_b32_e64 v121, 0, v121, s[74:75]
	s_waitcnt lgkmcnt(5)
	v_mfma_f32_32x32x16_bf16 v[132:147], v[156:159], v[200:203], v[132:147]
	ds_write_b128 v166, v[56:59] offset:1088
	ds_write_b128 v166, v[60:63] offset:1360
	v_cndmask_b32_e64 v122, 0, v122, s[76:77]
	v_cndmask_b32_e64 v123, 0, v123, s[78:79]
	v_cndmask_b32_e64 v124, 0, v124, s[80:81]
	v_cndmask_b32_e64 v125, 0, v125, s[82:83]
	v_cndmask_b32_e64 v126, 0, v126, s[84:85]
	v_cndmask_b32_e64 v127, 0, v127, s[86:87]
	v_cndmask_b32_e64 v128, 0, v128, s[88:89]
	v_cndmask_b32_e64 v129, 0, v129, s[90:91]
	v_cndmask_b32_e64 v130, 0, v130, s[92:93]
	s_waitcnt lgkmcnt(6)
	v_mfma_f32_32x32x16_bf16 v[132:147], v[160:163], v[204:207], v[132:147]
	ds_write_b128 v166, v[64:67] offset:1632
	ds_write_b128 v166, v[68:71] offset:1904
	v_cndmask_b32_e64 v131, 0, v131, s[94:95]
	v_cvt_pk_bf16_f32 v116, v116, v117
	v_cvt_pk_bf16_f32 v117, v118, v119
	v_cvt_pk_bf16_f32 v118, v120, v121
	v_cvt_pk_bf16_f32 v119, v122, v123
	v_cvt_pk_bf16_f32 v120, v124, v125
	v_cvt_pk_bf16_f32 v121, v126, v127
	v_cvt_pk_bf16_f32 v122, v128, v129
	v_cvt_pk_bf16_f32 v123, v130, v131
	global_load_dwordx4 v[40:43], v164, s[38:39] offset:0
	global_load_dwordx4 v[44:47], v164, s[38:39] offset:512
	global_load_dwordx4 v[48:51], v164, s[38:39] offset:1024
	global_load_dwordx4 v[52:55], v164, s[38:39] offset:1536
	global_load_dwordx4 v[56:59], v164, s[38:39] offset:2048
	global_load_dwordx4 v[60:63], v164, s[38:39] offset:2560
	global_load_dwordx4 v[64:67], v164, s[38:39] offset:3072
	global_load_dwordx4 v[68:71], v164, s[38:39] offset:3584
	s_add_u32 s38, s38, s46
	s_addc_u32 s39, s39, s55
	s_waitcnt lgkmcnt(0)
	ds_read_b128 v[234:237], v208 offset:0
	ds_read_b128 v[238:241], v208 offset:32
	ds_read_b128 v[242:245], v208 offset:64
	ds_read_b128 v[246:249], v208 offset:96
	ds_read_b32 v251, v216
	v_mfma_f32_32x32x16_bf16 v[76:91], v[36:39], v[116:119], 0
	v_mfma_f32_32x32x16_bf16 v[76:91], v[72:75], v[120:123], v[76:91]
	s_cmp_eq_u32 s52, 2
	s_cbranch_scc1 .Lm_yfin2_20
	ds_read_b64_tr_b16 v[36:37], v225 offset:0
	ds_read_b64_tr_b16 v[38:39], v225 offset:512
	ds_read_b64_tr_b16 v[72:73], v225 offset:1024
	ds_read_b64_tr_b16 v[74:75], v225 offset:1536
	v_add_u32_e32 v223, s53, v223
	v_add_u32_e32 v208, s54, v208
	v_add_u32_e32 v216, s54, v216
	v_add_u32_e32 v225, s13, v225
	s_waitcnt lgkmcnt(4)
	ds_read_b128 v[148:151], v223 offset:0
	ds_read_b128 v[152:155], v223 offset:32
	ds_read_b128 v[156:159], v223 offset:64
	ds_read_b128 v[160:163], v223 offset:96
	s_waitcnt lgkmcnt(3)
	v_mfma_f32_32x32x16_bf16 v[116:131], v[148:151], v[176:179], 0
	ds_read_b128 v[148:151], v223 offset:128
	v_sub_f32_e32 v2, v250, v251
	v_exp_f32_e32 v2, v2
	s_nop 0
	v_mul_f32_e32 v234, v234, v2
	v_mul_f32_e32 v235, v235, v2
	s_waitcnt lgkmcnt(3)
	v_mfma_f32_32x32x16_bf16 v[116:131], v[152:155], v[180:183], v[116:131]
	ds_read_b128 v[152:155], v223 offset:160
	v_mul_f32_e32 v236, v236, v2
	v_mul_f32_e32 v237, v237, v2
	v_mul_f32_e32 v238, v238, v2
	v_mul_f32_e32 v239, v239, v2
	v_mul_f32_e32 v240, v240, v2
	s_waitcnt lgkmcnt(3)
	v_mfma_f32_32x32x16_bf16 v[116:131], v[156:159], v[184:187], v[116:131]
	ds_read_b128 v[156:159], v223 offset:192
	v_mul_f32_e32 v241, v241, v2
	v_mul_f32_e32 v242, v242, v2
	v_mul_f32_e32 v243, v243, v2
	v_mul_f32_e32 v244, v244, v2
	v_mul_f32_e32 v245, v245, v2
	v_mul_f32_e32 v246, v246, v2
	s_waitcnt lgkmcnt(3)
	v_mfma_f32_32x32x16_bf16 v[116:131], v[160:163], v[188:191], v[116:131]
	ds_read_b128 v[160:163], v223 offset:224
	v_mul_f32_e32 v247, v247, v2
	v_mul_f32_e32 v248, v248, v2
	v_mul_f32_e32 v249, v249, v2
	v_mul_f32_e32 v132, v132, v234
	v_mul_f32_e32 v133, v133, v235
	s_waitcnt lgkmcnt(3)
	v_mfma_f32_32x32x16_bf16 v[116:131], v[148:151], v[192:195], v[116:131]
	v_mul_f32_e32 v134, v134, v236
	v_mul_f32_e32 v135, v135, v237
	v_mul_f32_e32 v136, v136, v238
	v_mul_f32_e32 v137, v137, v239
	v_mul_f32_e32 v138, v138, v240
	s_waitcnt lgkmcnt(2)
	v_mfma_f32_32x32x16_bf16 v[116:131], v[152:155], v[196:199], v[116:131]
	v_mul_f32_e32 v139, v139, v241
	v_mul_f32_e32 v140, v140, v242
	v_mul_f32_e32 v141, v141, v243
	v_mul_f32_e32 v142, v142, v244
	v_mul_f32_e32 v143, v143, v245
	v_mul_f32_e32 v144, v144, v246
	s_waitcnt lgkmcnt(1)
	v_mfma_f32_32x32x16_bf16 v[116:131], v[156:159], v[200:203], v[116:131]
	v_mul_f32_e32 v145, v145, v247
	v_mul_f32_e32 v146, v146, v248
	v_mul_f32_e32 v147, v147, v249
	v_cvt_pk_bf16_f32 v132, v132, v133
	v_cvt_pk_bf16_f32 v133, v134, v135
	s_waitcnt lgkmcnt(0)
	v_mfma_f32_32x32x16_bf16 v[116:131], v[160:163], v[204:207], v[116:131]
	v_cvt_pk_bf16_f32 v134, v136, v137
	v_cvt_pk_bf16_f32 v135, v138, v139
	v_cvt_pk_bf16_f32 v136, v140, v141
	v_cvt_pk_bf16_f32 v137, v142, v143
	v_cvt_pk_bf16_f32 v138, v144, v145
	v_cvt_pk_bf16_f32 v139, v146, v147
	ds_read_b128 v[234:237], v208 offset:0
	ds_read_b128 v[238:241], v208 offset:32
	ds_read_b128 v[242:245], v208 offset:64
	ds_read_b128 v[246:249], v208 offset:96
	ds_read_b32 v251, v216
	v_mfma_f32_32x32x16_bf16 v[76:91], v[36:39], v[132:135], v[76:91]
	v_mfma_f32_32x32x16_bf16 v[76:91], v[72:75], v[136:139], v[76:91]
	s_cmp_eq_u32 s52, 3
	s_cbranch_scc1 .Lm_yfin3_21
	ds_read_b64_tr_b16 v[36:37], v225 offset:0
	ds_read_b64_tr_b16 v[38:39], v225 offset:512
	ds_read_b64_tr_b16 v[72:73], v225 offset:1024
	ds_read_b64_tr_b16 v[74:75], v225 offset:1536
	v_add_u32_e32 v223, s53, v223
	v_add_u32_e32 v208, s54, v208
	v_add_u32_e32 v216, s54, v216
	v_add_u32_e32 v225, s13, v225
	s_waitcnt lgkmcnt(4)
	ds_read_b128 v[148:151], v223 offset:0
	ds_read_b128 v[152:155], v223 offset:32
	ds_read_b128 v[156:159], v223 offset:64
	ds_read_b128 v[160:163], v223 offset:96
	s_waitcnt lgkmcnt(3)
	v_mfma_f32_32x32x16_bf16 v[132:147], v[148:151], v[176:179], 0
	ds_read_b128 v[148:151], v223 offset:128
	v_sub_f32_e32 v2, v250, v251
	v_exp_f32_e32 v2, v2
	s_nop 0
	v_mul_f32_e32 v234, v234, v2
	v_mul_f32_e32 v235, v235, v2
	s_waitcnt lgkmcnt(3)
	v_mfma_f32_32x32x16_bf16 v[132:147], v[152:155], v[180:183], v[132:147]
	ds_read_b128 v[152:155], v223 offset:160
	v_mul_f32_e32 v236, v236, v2
	v_mul_f32_e32 v237, v237, v2
	v_mul_f32_e32 v238, v238, v2
	v_mul_f32_e32 v239, v239, v2
	v_mul_f32_e32 v240, v240, v2
	s_waitcnt lgkmcnt(3)
	v_mfma_f32_32x32x16_bf16 v[132:147], v[156:159], v[184:187], v[132:147]
	ds_read_b128 v[156:159], v223 offset:192
	v_mul_f32_e32 v241, v241, v2
	v_mul_f32_e32 v242, v242, v2
	v_mul_f32_e32 v243, v243, v2
	v_mul_f32_e32 v244, v244, v2
	v_mul_f32_e32 v245, v245, v2
	v_mul_f32_e32 v246, v246, v2
	s_waitcnt lgkmcnt(3)
	v_mfma_f32_32x32x16_bf16 v[132:147], v[160:163], v[188:191], v[132:147]
	ds_read_b128 v[160:163], v223 offset:224
	v_mul_f32_e32 v247, v247, v2
	v_mul_f32_e32 v248, v248, v2
	v_mul_f32_e32 v249, v249, v2
	v_mul_f32_e32 v116, v116, v234
	v_mul_f32_e32 v117, v117, v235
	s_waitcnt lgkmcnt(3)
	v_mfma_f32_32x32x16_bf16 v[132:147], v[148:151], v[192:195], v[132:147]
	v_mul_f32_e32 v118, v118, v236
	v_mul_f32_e32 v119, v119, v237
	v_mul_f32_e32 v120, v120, v238
	v_mul_f32_e32 v121, v121, v239
	v_mul_f32_e32 v122, v122, v240
	s_waitcnt lgkmcnt(2)
	v_mfma_f32_32x32x16_bf16 v[132:147], v[152:155], v[196:199], v[132:147]
	v_mul_f32_e32 v123, v123, v241
	v_mul_f32_e32 v124, v124, v242
	v_mul_f32_e32 v125, v125, v243
	v_mul_f32_e32 v126, v126, v244
	v_mul_f32_e32 v127, v127, v245
	v_mul_f32_e32 v128, v128, v246
	s_waitcnt lgkmcnt(1)
	v_mfma_f32_32x32x16_bf16 v[132:147], v[156:159], v[200:203], v[132:147]
	v_mul_f32_e32 v129, v129, v247
	v_mul_f32_e32 v130, v130, v248
	v_mul_f32_e32 v131, v131, v249
	v_cvt_pk_bf16_f32 v116, v116, v117
	v_cvt_pk_bf16_f32 v117, v118, v119
	s_waitcnt lgkmcnt(0)
	v_mfma_f32_32x32x16_bf16 v[132:147], v[160:163], v[204:207], v[132:147]
	v_cvt_pk_bf16_f32 v118, v120, v121
	v_cvt_pk_bf16_f32 v119, v122, v123
	v_cvt_pk_bf16_f32 v120, v124, v125
	v_cvt_pk_bf16_f32 v121, v126, v127
	v_cvt_pk_bf16_f32 v122, v128, v129
	v_cvt_pk_bf16_f32 v123, v130, v131
	ds_read_b128 v[234:237], v208 offset:0
	ds_read_b128 v[238:241], v208 offset:32
	ds_read_b128 v[242:245], v208 offset:64
	ds_read_b128 v[246:249], v208 offset:96
	ds_read_b32 v251, v216
	v_mfma_f32_32x32x16_bf16 v[76:91], v[36:39], v[116:119], v[76:91]
	v_mfma_f32_32x32x16_bf16 v[76:91], v[72:75], v[120:123], v[76:91]
	ds_read_b64_tr_b16 v[36:37], v225 offset:0
	ds_read_b64_tr_b16 v[38:39], v225 offset:512
	ds_read_b64_tr_b16 v[72:73], v225 offset:1024
	ds_read_b64_tr_b16 v[74:75], v225 offset:1536
	s_waitcnt lgkmcnt(4)
	ds_read_b128 v[148:151], v210 offset:0
	ds_read_b128 v[152:155], v210 offset:32
	ds_read_b128 v[156:159], v210 offset:64
	ds_read_b128 v[160:163], v210 offset:96
	s_waitcnt lgkmcnt(3)
	v_mfma_f32_32x32x16_bf16 v[92:107], v[148:151], v[176:179], 0
	ds_read_b128 v[148:151], v210 offset:128
	v_sub_f32_e32 v2, v250, v251
	v_exp_f32_e32 v2, v2
	s_nop 0
	v_mul_f32_e32 v234, v234, v2
	v_mul_f32_e32 v235, v235, v2
	s_waitcnt lgkmcnt(3)
	v_mfma_f32_32x32x16_bf16 v[92:107], v[152:155], v[180:183], v[92:107]
	ds_read_b128 v[152:155], v210 offset:160
	v_mul_f32_e32 v236, v236, v2
	v_mul_f32_e32 v237, v237, v2
	v_mul_f32_e32 v238, v238, v2
	v_mul_f32_e32 v239, v239, v2
	v_mul_f32_e32 v240, v240, v2
	s_waitcnt lgkmcnt(3)
	v_mfma_f32_32x32x16_bf16 v[92:107], v[156:159], v[184:187], v[92:107]
	ds_read_b128 v[156:159], v210 offset:192
	v_mul_f32_e32 v241, v241, v2
	v_mul_f32_e32 v242, v242, v2
	v_mul_f32_e32 v243, v243, v2
	v_mul_f32_e32 v244, v244, v2
	v_mul_f32_e32 v245, v245, v2
	v_mul_f32_e32 v246, v246, v2
	s_waitcnt lgkmcnt(3)
	v_mfma_f32_32x32x16_bf16 v[92:107], v[160:163], v[188:191], v[92:107]
	ds_read_b128 v[160:163], v210 offset:224
	v_mul_f32_e32 v247, v247, v2
	v_mul_f32_e32 v248, v248, v2
	v_mul_f32_e32 v249, v249, v2
	v_mul_f32_e32 v132, v132, v234
	v_mul_f32_e32 v133, v133, v235
	s_waitcnt lgkmcnt(3)
	v_mfma_f32_32x32x16_bf16 v[92:107], v[148:151], v[192:195], v[92:107]
	v_mul_f32_e32 v134, v134, v236
	v_mul_f32_e32 v135, v135, v237
	v_mul_f32_e32 v136, v136, v238
	v_mul_f32_e32 v137, v137, v239
	v_mul_f32_e32 v138, v138, v240
	s_waitcnt lgkmcnt(2)
	v_mfma_f32_32x32x16_bf16 v[92:107], v[152:155], v[196:199], v[92:107]
	v_mul_f32_e32 v139, v139, v241
	v_mul_f32_e32 v140, v140, v242
	v_mul_f32_e32 v141, v141, v243
	v_mul_f32_e32 v142, v142, v244
	v_mul_f32_e32 v143, v143, v245
	v_mul_f32_e32 v144, v144, v246
	s_waitcnt lgkmcnt(1)
	v_mfma_f32_32x32x16_bf16 v[92:107], v[156:159], v[200:203], v[92:107]
	v_mul_f32_e32 v145, v145, v247
	v_mul_f32_e32 v146, v146, v248
	v_mul_f32_e32 v147, v147, v249
	v_cvt_pk_bf16_f32 v132, v132, v133
	v_cvt_pk_bf16_f32 v133, v134, v135
	s_waitcnt lgkmcnt(0)
	v_mfma_f32_32x32x16_bf16 v[92:107], v[160:163], v[204:207], v[92:107]
	v_cvt_pk_bf16_f32 v134, v136, v137
	v_cvt_pk_bf16_f32 v135, v138, v139
	v_cvt_pk_bf16_f32 v136, v140, v141
	v_cvt_pk_bf16_f32 v137, v142, v143
	v_cvt_pk_bf16_f32 v138, v144, v145
	v_cvt_pk_bf16_f32 v139, v146, v147
	v_mfma_f32_32x32x16_bf16 v[76:91], v[36:39], v[132:135], v[76:91]
	v_mfma_f32_32x32x16_bf16 v[76:91], v[72:75], v[136:139], v[76:91]
	s_branch .Lm_ydone_22
.Lm_yfin1_19:
	ds_write_b128 v168, v[76:79] offset:0
	ds_write_b128 v168, v[80:83] offset:32
	ds_write_b128 v168, v[84:87] offset:64
	ds_write_b128 v168, v[88:91] offset:96
	s_waitcnt lgkmcnt(0)
	ds_read_b128 v[92:95], v169 offset:0
	ds_read_b128 v[96:99], v169 offset:16
	ds_read_b128 v[100:103], v169 offset:2304
	ds_read_b128 v[104:107], v169 offset:2320
	s_waitcnt lgkmcnt(0)
	v_cvt_pk_bf16_f32 v92, v92, v93
	v_cvt_pk_bf16_f32 v93, v94, v95
	v_cvt_pk_bf16_f32 v94, v96, v97
	v_cvt_pk_bf16_f32 v95, v98, v99
	v_cvt_pk_bf16_f32 v100, v100, v101
	v_cvt_pk_bf16_f32 v101, v102, v103
	v_cvt_pk_bf16_f32 v102, v104, v105
	v_cvt_pk_bf16_f32 v103, v106, v107
	global_store_dwordx4 v170, v[92:95], s[44:45]
	global_store_dwordx4 v171, v[100:103], s[44:45]
	s_cmp_lg_u32 s50, 0
	s_cselect_b32 s4, s49, 0
	s_cselect_b32 s5, s55, 0
	s_cselect_b32 s6, s47, 0
	s_add_u32 s44, s44, s4
	s_addc_u32 s45, s45, s5
	s_add_u32 s40, s40, s6
	s_addc_u32 s41, s41, s5
	s_waitcnt vmcnt(16)
	ds_write_b128 v166, v[40:43] offset:0
	ds_write_b128 v166, v[44:47] offset:272
	ds_write_b128 v166, v[48:51] offset:544
	ds_write_b128 v166, v[52:55] offset:816
	ds_write_b128 v166, v[56:59] offset:1088
	ds_write_b128 v166, v[60:63] offset:1360
	ds_write_b128 v166, v[64:67] offset:1632
	ds_write_b128 v166, v[68:71] offset:1904
	global_load_dwordx4 v[40:43], v164, s[38:39] offset:0
	global_load_dwordx4 v[44:47], v164, s[38:39] offset:512
	global_load_dwordx4 v[48:51], v164, s[38:39] offset:1024
	global_load_dwordx4 v[52:55], v164, s[38:39] offset:1536
	global_load_dwordx4 v[56:59], v164, s[38:39] offset:2048
	global_load_dwordx4 v[60:63], v164, s[38:39] offset:2560
	global_load_dwordx4 v[64:67], v164, s[38:39] offset:3072
	global_load_dwordx4 v[68:71], v164, s[38:39] offset:3584
	s_add_u32 s38, s38, s46
	s_addc_u32 s39, s39, s55
	s_waitcnt lgkmcnt(0)
	ds_read_b64_tr_b16 v[36:37], v225 offset:0
	ds_read_b64_tr_b16 v[38:39], v225 offset:512
	ds_read_b64_tr_b16 v[72:73], v225 offset:1024
	ds_read_b64_tr_b16 v[74:75], v225 offset:1536
	ds_read_b128 v[148:151], v210 offset:0
	ds_read_b128 v[152:155], v210 offset:32
	ds_read_b128 v[156:159], v210 offset:64
	ds_read_b128 v[160:163], v210 offset:96
	s_waitcnt lgkmcnt(3)
	v_mfma_f32_32x32x16_bf16 v[92:107], v[148:151], v[176:179], 0
	ds_read_b128 v[148:151], v210 offset:128
	v_sub_f32_e32 v234, v250, v234
	v_sub_f32_e32 v235, v250, v235
	v_sub_f32_e32 v236, v250, v236
	v_sub_f32_e32 v237, v250, v237
	v_sub_f32_e32 v238, v250, v238
	v_sub_f32_e32 v239, v250, v239
	v_sub_f32_e32 v240, v250, v240
	v_sub_f32_e32 v241, v250, v241
	v_sub_f32_e32 v242, v250, v242
	s_waitcnt lgkmcnt(3)
	v_mfma_f32_32x32x16_bf16 v[92:107], v[152:155], v[180:183], v[92:107]
	ds_read_b128 v[152:155], v210 offset:160
	v_sub_f32_e32 v243, v250, v243
	v_sub_f32_e32 v244, v250, v244
	v_sub_f32_e32 v245, v250, v245
	v_sub_f32_e32 v246, v250, v246
	v_sub_f32_e32 v247, v250, v247
	v_sub_f32_e32 v248, v250, v248
	v_sub_f32_e32 v249, v250, v249
	v_exp_f32_e32 v234, v234
	v_exp_f32_e32 v235, v235
	s_waitcnt lgkmcnt(3)
	v_mfma_f32_32x32x16_bf16 v[92:107], v[156:159], v[184:187], v[92:107]
	ds_read_b128 v[156:159], v210 offset:192
	v_exp_f32_e32 v236, v236
	v_exp_f32_e32 v237, v237
	v_exp_f32_e32 v238, v238
	v_exp_f32_e32 v239, v239
	v_exp_f32_e32 v240, v240
	v_exp_f32_e32 v241, v241
	v_exp_f32_e32 v242, v242
	v_exp_f32_e32 v243, v243
	v_exp_f32_e32 v244, v244
	s_waitcnt lgkmcnt(3)
	v_mfma_f32_32x32x16_bf16 v[92:107], v[160:163], v[188:191], v[92:107]
	ds_read_b128 v[160:163], v210 offset:224
	v_exp_f32_e32 v245, v245
	v_exp_f32_e32 v246, v246
	v_exp_f32_e32 v247, v247
	v_exp_f32_e32 v248, v248
	v_exp_f32_e32 v249, v249
	v_mul_f32_e32 v116, v116, v234
	v_mul_f32_e32 v117, v117, v235
	v_mul_f32_e32 v118, v118, v236
	v_mul_f32_e32 v119, v119, v237
	s_waitcnt lgkmcnt(3)
	v_mfma_f32_32x32x16_bf16 v[92:107], v[148:151], v[192:195], v[92:107]
	v_mul_f32_e32 v120, v120, v238
	v_mul_f32_e32 v121, v121, v239
	v_mul_f32_e32 v122, v122, v240
	v_mul_f32_e32 v123, v123, v241
	v_mul_f32_e32 v124, v124, v242
	v_mul_f32_e32 v125, v125, v243
	v_mul_f32_e32 v126, v126, v244
	v_mul_f32_e32 v127, v127, v245
	v_mul_f32_e32 v128, v128, v246
	s_waitcnt lgkmcnt(2)
	v_mfma_f32_32x32x16_bf16 v[92:107], v[152:155], v[196:199], v[92:107]
	v_mul_f32_e32 v129, v129, v247
	v_mul_f32_e32 v130, v130, v248
	v_mul_f32_e32 v131, v131, v249
	v_cndmask_b32_e64 v116, 0, v116, s[64:65]
	v_cndmask_b32_e64 v117, 0, v117, s[66:67]
	v_cndmask_b32_e64 v118, 0, v118, s[68:69]
	v_cndmask_b32_e64 v119, 0, v119, s[70:71]
	v_cndmask_b32_e64 v120, 0, v120, s[72:73]
	v_cndmask_b32_e64 v121, 0, v121, s[74:75]
	s_waitcnt lgkmcnt(1)
	v_mfma_f32_32x32x16_bf16 v[92:107], v[156:159], v[200:203], v[92:107]
	v_cndmask_b32_e64 v122, 0, v122, s[76:77]
	v_cndmask_b32_e64 v123, 0, v123, s[78:79]
	v_cndmask_b32_e64 v124, 0, v124, s[80:81]
	v_cndmask_b32_e64 v125, 0, v125, s[82:83]
	v_cndmask_b32_e64 v126, 0, v126, s[84:85]
	v_cndmask_b32_e64 v127, 0, v127, s[86:87]
	v_cndmask_b32_e64 v128, 0, v128, s[88:89]
	v_cndmask_b32_e64 v129, 0, v129, s[90:91]
	v_cndmask_b32_e64 v130, 0, v130, s[92:93]
	s_waitcnt lgkmcnt(0)
	v_mfma_f32_32x32x16_bf16 v[92:107], v[160:163], v[204:207], v[92:107]
	v_cndmask_b32_e64 v131, 0, v131, s[94:95]
	v_cvt_pk_bf16_f32 v116, v116, v117
	v_cvt_pk_bf16_f32 v117, v118, v119
	v_cvt_pk_bf16_f32 v118, v120, v121
	v_cvt_pk_bf16_f32 v119, v122, v123
	v_cvt_pk_bf16_f32 v120, v124, v125
	v_cvt_pk_bf16_f32 v121, v126, v127
	v_cvt_pk_bf16_f32 v122, v128, v129
	v_cvt_pk_bf16_f32 v123, v130, v131
	v_mfma_f32_32x32x16_bf16 v[76:91], v[36:39], v[116:119], 0
	v_mfma_f32_32x32x16_bf16 v[76:91], v[72:75], v[120:123], v[76:91]
	s_waitcnt vmcnt(10)
	v_mul_f32_e32 v132, s62, v146
	v_mul_f32_e32 v133, s62, v147
	v_add_f32_e32 v134, v132, v133
	v_and_b32_e32 v140, 63, v175
	v_lshrrev_b32_e32 v142, 4, v140
	v_add_f32_dpp v134, v134, v134 row_shr:1 row_mask:0xf bank_mask:0xf bound_ctrl:0
	s_nop 1
	v_add_f32_dpp v134, v134, v134 row_shr:2 row_mask:0xf bank_mask:0xf bound_ctrl:0
	s_nop 1
	v_add_f32_dpp v134, v134, v134 row_shr:4 row_mask:0xf bank_mask:0xf bound_ctrl:0
	s_nop 1
	v_add_f32_dpp v134, v134, v134 row_shr:8 row_mask:0xf bank_mask:0xf bound_ctrl:0
	s_nop 1
	v_add_f32_dpp v134, v134, v134 row_bcast:15 row_mask:0xa bank_mask:0xf
	s_nop 1
	v_add_f32_dpp v134, v134, v134 row_bcast:31 row_mask:0xc bank_mask:0xf
	v_lshlrev_b32_e32 v140, 3, v140
	v_lshlrev_b32_e32 v142, 7, v142
	v_readlane_b32 s97, v134, 63
	v_sub_f32_e32 v138, v134, v133
	v_mov_b32_e32 v139, v134
	v_add_u32_e32 v143, 0x1d800, v140
	v_add_u32_e32 v143, s20, v143
	s_cmp_eq_u32 s51, 0
	s_cbranch_scc1 .Lm_scanf_23
	v_sub_f32_e32 v138, s97, v138
	v_sub_f32_e32 v139, s97, v139
	v_fma_f32 v138, v146, s62, v138
	v_fma_f32 v139, v147, s62, v139

.Lm_stepdone_26:
	s_waitcnt lgkmcnt(0)
	s_barrier
	s_mov_b32 s14, s16
	s_mov_b32 s16, s17
	s_add_u32 s17, s17, 1280
	s_cmpk_eq_u32 s17, 5120
	s_cselect_b32 s17, 0, s17
	s_add_u32 s50, s50, 1
	s_cmp_lt_u32 s50, 64
	s_cbranch_scc1 .Lm_loop
	s_cmp_lt_u32 s3, 4
	s_cbranch_scc0 .Lm_noflush_36
	s_nop 7
	s_nop 3
	v_fma_f32 v76, v92, v3, v76
	v_fma_f32 v77, v93, v3, v77
	v_fma_f32 v78, v94, v3, v78
	v_fma_f32 v79, v95, v3, v79
	v_fma_f32 v80, v96, v3, v80
	v_fma_f32 v81, v97, v3, v81
	v_fma_f32 v82, v98, v3, v82
	v_fma_f32 v83, v99, v3, v83
	v_fma_f32 v84, v100, v3, v84
	v_fma_f32 v85, v101, v3, v85
	v_fma_f32 v86, v102, v3, v86
	v_fma_f32 v87, v103, v3, v87
	v_fma_f32 v88, v104, v3, v88
	v_fma_f32 v89, v105, v3, v89
	v_fma_f32 v90, v106, v3, v90
	v_fma_f32 v91, v107, v3, v91
	ds_write_b128 v168, v[76:79] offset:0
	ds_write_b128 v168, v[80:83] offset:32
	ds_write_b128 v168, v[84:87] offset:64
	ds_write_b128 v168, v[88:91] offset:96
	s_waitcnt lgkmcnt(0)
	ds_read_b128 v[92:95], v169 offset:0
	ds_read_b128 v[96:99], v169 offset:16
	ds_read_b128 v[100:103], v169 offset:2304
	ds_read_b128 v[104:107], v169 offset:2320
	s_waitcnt vmcnt(0) lgkmcnt(0)
	v_cvt_pk_bf16_f32 v92, v92, v93
	v_cvt_pk_bf16_f32 v93, v94, v95
	v_cvt_pk_bf16_f32 v94, v96, v97
	v_cvt_pk_bf16_f32 v95, v98, v99
	v_cvt_pk_bf16_f32 v100, v100, v101
	v_cvt_pk_bf16_f32 v101, v102, v103
	v_cvt_pk_bf16_f32 v102, v104, v105
	v_cvt_pk_bf16_f32 v103, v106, v107
	global_store_dwordx4 v170, v[92:95], s[44:45]
	global_store_dwordx4 v171, v[100:103], s[44:45]
